# v38 plus counted vmcnt waits ordering each half's gate-row loads before first use (formal safety, no schedule change)
# speedup vs baseline: 1.0155x; 1.0155x over previous
.LBB0_295:
	ds_read_b128 v[130:133], v188
	ds_read_b128 v[134:137], v188 offset:16
	ds_read_b128 v[138:141], v188 offset:256
	ds_read_b128 v[142:145], v188 offset:272
	ds_read_b128 v[146:149], v188 offset:512
	ds_read_b128 v[150:153], v188 offset:528
	ds_read_b128 v[154:157], v188 offset:768
	ds_read_b128 v[166:169], v188 offset:784
	s_sub_i32 s0, s8, s25
	v_cmp_gt_i32_e32 vcc, s26, v175
	s_min_i32 s1, s24, s20
	s_lshl_b32 s1, s1, 5
	s_sub_i32 s25, s17, s1
	v_lshlrev_b32_e32 v172, 16, v126
	v_and_b32_e32 v173, 0xffff0000, v126
	s_cmp_gt_i32 s25, 31
	s_waitcnt lgkmcnt(6)
	v_mul_f32_e32 v238, v130, v130
	v_mul_f32_e32 v239, v131, v131
	v_mul_f32_e32 v240, v132, v132
	v_mul_f32_e32 v241, v133, v133
	v_fmac_f32_e32 v238, v134, v134
	v_fmac_f32_e32 v239, v135, v135
	v_fmac_f32_e32 v240, v136, v136
	v_fmac_f32_e32 v241, v137, v137
	s_waitcnt lgkmcnt(4)
	v_fmac_f32_e32 v238, v138, v138
	v_fmac_f32_e32 v239, v139, v139
	v_fmac_f32_e32 v240, v140, v140
	v_fmac_f32_e32 v241, v141, v141
	v_fmac_f32_e32 v238, v142, v142
	v_fmac_f32_e32 v239, v143, v143
	v_fmac_f32_e32 v240, v144, v144
	v_fmac_f32_e32 v241, v145, v145
	s_waitcnt lgkmcnt(2)
	v_fmac_f32_e32 v238, v146, v146
	v_fmac_f32_e32 v239, v147, v147
	v_fmac_f32_e32 v240, v148, v148
	v_fmac_f32_e32 v241, v149, v149
	v_fmac_f32_e32 v238, v150, v150
	v_fmac_f32_e32 v239, v151, v151
	v_fmac_f32_e32 v240, v152, v152
	v_fmac_f32_e32 v241, v153, v153
	s_waitcnt lgkmcnt(0)
	v_fmac_f32_e32 v238, v154, v154
	v_fmac_f32_e32 v239, v155, v155
	v_fmac_f32_e32 v240, v156, v156
	v_fmac_f32_e32 v241, v157, v157
	v_fmac_f32_e32 v238, v166, v166
	v_fmac_f32_e32 v239, v167, v167
	v_fmac_f32_e32 v240, v168, v168
	v_fmac_f32_e32 v241, v169, v169
	v_add_f32_e32 v238, v238, v239
	v_add_f32_e32 v240, v240, v241
	v_add_f32_e32 v158, v238, v240
	s_nop 1
	v_add_f32_dpp v158, v158, v158 quad_perm:[1,0,3,2] row_mask:0xf bank_mask:0xf
	s_nop 1
	v_add_f32_dpp v158, v158, v158 quad_perm:[2,3,0,1] row_mask:0xf bank_mask:0xf
	s_nop 1
	v_add_f32_dpp v158, v158, v158 row_half_mirror row_mask:0xf bank_mask:0xf
	v_fmamk_f32 v158, v158, 0x3b800000, v206
	v_rsq_f32_e32 v158, v158
	s_waitcnt vmcnt(58)
	v_mov_b32_e32 v159, s0
	v_cndmask_b32_e32 v159, v210, v159, vcc
	v_add_u32_e32 v170, v159, v175
	v_ashrrev_i32_e32 v171, 31, v170
	v_lshlrev_b64 v[170:171], 13, v[170:171]
	v_lshl_add_u64 v[170:171], v[74:75], 0, v[170:171]
	v_pk_mul_f32 v[130:131], v[130:131], v[158:159] op_sel_hi:[1,0]
	v_lshlrev_b32_e32 v238, 16, v80
	v_and_b32_e32 v239, 0xffff0000, v80
	v_pk_mul_f32 v[130:131], v[130:131], v[238:239]
	v_cvt_pk_bf16_f32 v80, v130, v131
	v_pk_mul_f32 v[132:133], v[132:133], v[158:159] op_sel_hi:[1,0]
	v_lshlrev_b32_e32 v238, 16, v81
	v_and_b32_e32 v239, 0xffff0000, v81
	v_pk_mul_f32 v[132:133], v[132:133], v[238:239]
	v_cvt_pk_bf16_f32 v81, v132, v133
	v_pk_mul_f32 v[134:135], v[134:135], v[158:159] op_sel_hi:[1,0]
	v_lshlrev_b32_e32 v238, 16, v82
	v_and_b32_e32 v239, 0xffff0000, v82
	v_pk_mul_f32 v[134:135], v[134:135], v[238:239]
	v_cvt_pk_bf16_f32 v82, v134, v135
	v_pk_mul_f32 v[136:137], v[136:137], v[158:159] op_sel_hi:[1,0]
	v_lshlrev_b32_e32 v238, 16, v83
	v_and_b32_e32 v239, 0xffff0000, v83
	v_pk_mul_f32 v[136:137], v[136:137], v[238:239]
	v_cvt_pk_bf16_f32 v83, v136, v137
	global_store_dwordx4 v[170:171], v[80:83], off
	v_pk_mul_f32 v[138:139], v[138:139], v[158:159] op_sel_hi:[1,0]
	v_lshlrev_b32_e32 v238, 16, v84
	v_and_b32_e32 v239, 0xffff0000, v84
	v_pk_mul_f32 v[138:139], v[138:139], v[238:239]
	v_cvt_pk_bf16_f32 v84, v138, v139
	v_pk_mul_f32 v[140:141], v[140:141], v[158:159] op_sel_hi:[1,0]
	v_lshlrev_b32_e32 v238, 16, v85
	v_and_b32_e32 v239, 0xffff0000, v85
	v_pk_mul_f32 v[140:141], v[140:141], v[238:239]
	v_cvt_pk_bf16_f32 v85, v140, v141
	v_pk_mul_f32 v[142:143], v[142:143], v[158:159] op_sel_hi:[1,0]
	v_lshlrev_b32_e32 v238, 16, v86
	v_and_b32_e32 v239, 0xffff0000, v86
	v_pk_mul_f32 v[142:143], v[142:143], v[238:239]
	v_cvt_pk_bf16_f32 v86, v142, v143
	v_pk_mul_f32 v[144:145], v[144:145], v[158:159] op_sel_hi:[1,0]
	v_lshlrev_b32_e32 v238, 16, v87
	v_and_b32_e32 v239, 0xffff0000, v87
	v_pk_mul_f32 v[144:145], v[144:145], v[238:239]
	v_cvt_pk_bf16_f32 v87, v144, v145
	global_store_dwordx4 v[170:171], v[84:87], off offset:128
	v_pk_mul_f32 v[146:147], v[146:147], v[158:159] op_sel_hi:[1,0]
	v_lshlrev_b32_e32 v238, 16, v92
	v_and_b32_e32 v239, 0xffff0000, v92
	v_pk_mul_f32 v[146:147], v[146:147], v[238:239]
	v_cvt_pk_bf16_f32 v92, v146, v147
	v_pk_mul_f32 v[148:149], v[148:149], v[158:159] op_sel_hi:[1,0]
	v_lshlrev_b32_e32 v238, 16, v93
	v_and_b32_e32 v239, 0xffff0000, v93
	v_pk_mul_f32 v[148:149], v[148:149], v[238:239]
	v_cvt_pk_bf16_f32 v93, v148, v149
	v_pk_mul_f32 v[150:151], v[150:151], v[158:159] op_sel_hi:[1,0]
	v_lshlrev_b32_e32 v238, 16, v94
	v_and_b32_e32 v239, 0xffff0000, v94
	v_pk_mul_f32 v[150:151], v[150:151], v[238:239]
	v_cvt_pk_bf16_f32 v94, v150, v151
	v_pk_mul_f32 v[152:153], v[152:153], v[158:159] op_sel_hi:[1,0]
	v_lshlrev_b32_e32 v238, 16, v95
	v_and_b32_e32 v239, 0xffff0000, v95
	v_pk_mul_f32 v[152:153], v[152:153], v[238:239]
	v_cvt_pk_bf16_f32 v95, v152, v153
	global_store_dwordx4 v[170:171], v[92:95], off offset:256
	v_pk_mul_f32 v[154:155], v[154:155], v[158:159] op_sel_hi:[1,0]
	v_lshlrev_b32_e32 v238, 16, v96
	v_and_b32_e32 v239, 0xffff0000, v96
	v_pk_mul_f32 v[154:155], v[154:155], v[238:239]
	v_cvt_pk_bf16_f32 v96, v154, v155
	v_pk_mul_f32 v[156:157], v[156:157], v[158:159] op_sel_hi:[1,0]
	v_lshlrev_b32_e32 v238, 16, v97
	v_and_b32_e32 v239, 0xffff0000, v97
	v_pk_mul_f32 v[156:157], v[156:157], v[238:239]
	v_cvt_pk_bf16_f32 v97, v156, v157
	v_pk_mul_f32 v[166:167], v[166:167], v[158:159] op_sel_hi:[1,0]
	v_lshlrev_b32_e32 v238, 16, v98
	v_and_b32_e32 v239, 0xffff0000, v98
	v_pk_mul_f32 v[166:167], v[166:167], v[238:239]
	v_cvt_pk_bf16_f32 v98, v166, v167
	v_pk_mul_f32 v[168:169], v[168:169], v[158:159] op_sel_hi:[1,0]
	v_lshlrev_b32_e32 v238, 16, v99
	v_and_b32_e32 v239, 0xffff0000, v99
	v_pk_mul_f32 v[168:169], v[168:169], v[238:239]
	v_cvt_pk_bf16_f32 v99, v168, v169
	global_store_dwordx4 v[170:171], v[96:99], off offset:384
	s_waitcnt vmcnt(4)
	v_lshlrev_b32_e32 v168, 16, v232
	v_add_u32_e32 v238, s1, v217
	v_ashrrev_i32_e32 v239, 31, v238
	v_lshlrev_b64 v[238:239], 13, v[238:239]
	v_lshl_add_u64 v[238:239], v[78:79], 0, v[238:239]
	global_load_dwordx4 v[80:83], v[238:239], off
	global_load_dwordx4 v[84:87], v[238:239], off offset:128
	global_load_dwordx4 v[92:95], v[238:239], off offset:256
	global_load_dwordx4 v[96:99], v[238:239], off offset:384
	s_mov_b64 s[0:1], -1
	v_lshlrev_b32_e32 v170, 16, v234
	v_lshlrev_b32_e32 v166, 16, v231
	v_lshlrev_b32_e32 v158, 16, v229
	s_cbranch_scc1 .LBB0_297
	s_min_i32 s0, s25, 32
	v_add_f32_e32 v130, 0, v106
	v_cmp_gt_i32_e32 vcc, s0, v176
	v_and_b32_e32 v132, 0xffff0000, v235
	v_and_b32_e32 v134, 0xffff0000, v234
	v_cndmask_b32_e32 v136, 0, v130, vcc
	v_add_f32_e32 v130, 0, v107
	v_cndmask_b32_e32 v139, 0, v130, vcc
	v_lshlrev_b32_e32 v130, 16, v233
	v_cndmask_b32_e32 v131, 0, v130, vcc
	v_and_b32_e32 v130, 0xffff0000, v233
	v_cndmask_b32_e32 v241, 0, v130, vcc
	v_cmp_gt_i32_e32 vcc, s0, v1
	v_lshlrev_b32_e32 v130, 16, v235
	v_and_b32_e32 v135, 0xffff0000, v232
	v_cndmask_b32_e32 v133, 0, v102, vcc
	v_add_f32_e32 v138, v136, v133
	v_cndmask_b32_e32 v239, 0, v130, vcc
	v_cndmask_b32_e32 v240, 0, v132, vcc
	v_cndmask_b32_e32 v133, 0, v103, vcc
	v_cmp_gt_i32_e32 vcc, s0, v40
	v_and_b32_e32 v137, 0xffff0000, v231
	v_and_b32_e32 v140, 0xffff0000, v229
	v_cndmask_b32_e32 v132, 0, v118, vcc
	v_cmp_gt_i32_e32 vcc, s0, v41
	v_pk_add_f32 v[146:147], v[132:133], v[138:139]
	v_lshlrev_b32_e32 v159, 16, v236
	v_cndmask_b32_e32 v157, 0, v134, vcc
	v_cndmask_b32_e32 v156, 0, v170, vcc
	v_cndmask_b32_e32 v133, 0, v119, vcc
	v_cmp_gt_i32_e32 vcc, s0, v54
	v_lshlrev_b32_e32 v162, 16, v237
	v_and_b32_e32 v163, 0xffff0000, v236
	v_cndmask_b32_e32 v132, 0, v114, vcc
	v_cmp_gt_i32_e32 vcc, s0, v3
	v_pk_add_f32 v[148:149], v[132:133], v[146:147]
	s_nop 0
	v_cndmask_b32_e32 v155, 0, v135, vcc
	v_cndmask_b32_e32 v154, 0, v168, vcc
	v_cndmask_b32_e32 v133, 0, v115, vcc
	v_cmp_gt_i32_e32 vcc, s0, v52
	s_nop 1
	v_cndmask_b32_e32 v132, 0, v100, vcc
	v_cmp_gt_i32_e32 vcc, s0, v43
	v_pk_add_f32 v[142:143], v[132:133], v[148:149]
	s_nop 0
	v_cndmask_b32_e32 v153, 0, v137, vcc
	v_cndmask_b32_e32 v152, 0, v166, vcc
	v_cndmask_b32_e32 v133, 0, v101, vcc
	v_cmp_gt_i32_e32 vcc, s0, v42
	s_nop 1
	v_cndmask_b32_e32 v132, 0, v90, vcc
	v_cmp_gt_i32_e32 vcc, s0, v51
	v_pk_add_f32 v[144:145], v[132:133], v[142:143]
	s_nop 0
	v_cndmask_b32_e32 v151, 0, v140, vcc
	v_cndmask_b32_e32 v150, 0, v158, vcc
	v_cndmask_b32_e32 v133, 0, v91, vcc
	v_cmp_gt_i32_e32 vcc, s0, v50
	s_nop 1
	v_cndmask_b32_e32 v132, 0, v108, vcc
	v_cmp_gt_i32_e32 vcc, s0, v45
	v_cmp_gt_i32_e64 s[0:1], s0, v44
	v_pk_add_f32 v[140:141], v[132:133], v[144:145]
	v_cndmask_b32_e32 v133, 0, v109, vcc
	v_cndmask_b32_e64 v132, 0, v128, s[0:1]
	v_cndmask_b32_e32 v130, 0, v159, vcc
	v_pk_add_f32 v[134:135], v[132:133], v[140:141]
	v_cndmask_b32_e64 v132, 0, v129, s[0:1]
	v_and_b32_e32 v159, 0xffff0000, v237
	v_add_f32_e32 v137, v132, v135
	v_cndmask_b32_e32 v133, 0, v163, vcc
	v_cndmask_b32_e64 v132, 0, v162, s[0:1]
	v_cndmask_b32_e64 v238, 0, v159, s[0:1]
	s_mov_b64 s[0:1], 0

.LBB0_305:
	ds_read_b128 v[130:133], v188 offset:33280
	ds_read_b128 v[134:137], v188 offset:33296
	ds_read_b128 v[138:141], v188 offset:33536
	ds_read_b128 v[142:145], v188 offset:33552
	ds_read_b128 v[146:149], v188 offset:33792
	ds_read_b128 v[150:153], v188 offset:33808
	ds_read_b128 v[154:157], v188 offset:34048
	ds_read_b128 v[166:169], v188 offset:34064
	s_sub_i32 s0, s21, s0
	v_cmp_gt_i32_e32 vcc, s1, v175
	s_add_i32 s10, s24, 1
	s_min_i32 s10, s10, s20
	v_lshlrev_b32_e32 v170, 16, v124
	v_and_b32_e32 v171, 0xffff0000, v124
	s_lshl_b32 s10, s10, 5
	s_waitcnt lgkmcnt(6)
	v_mul_f32_e32 v238, v130, v130
	v_mul_f32_e32 v239, v131, v131
	v_mul_f32_e32 v240, v132, v132
	v_mul_f32_e32 v241, v133, v133
	v_fmac_f32_e32 v238, v134, v134
	v_fmac_f32_e32 v239, v135, v135
	v_fmac_f32_e32 v240, v136, v136
	v_fmac_f32_e32 v241, v137, v137
	s_waitcnt lgkmcnt(4)
	v_fmac_f32_e32 v238, v138, v138
	v_fmac_f32_e32 v239, v139, v139
	v_fmac_f32_e32 v240, v140, v140
	v_fmac_f32_e32 v241, v141, v141
	v_fmac_f32_e32 v238, v142, v142
	v_fmac_f32_e32 v239, v143, v143
	v_fmac_f32_e32 v240, v144, v144
	v_fmac_f32_e32 v241, v145, v145
	s_waitcnt lgkmcnt(2)
	v_fmac_f32_e32 v238, v146, v146
	v_fmac_f32_e32 v239, v147, v147
	v_fmac_f32_e32 v240, v148, v148
	v_fmac_f32_e32 v241, v149, v149
	v_fmac_f32_e32 v238, v150, v150
	v_fmac_f32_e32 v239, v151, v151
	v_fmac_f32_e32 v240, v152, v152
	v_fmac_f32_e32 v241, v153, v153
	s_waitcnt lgkmcnt(0)
	v_fmac_f32_e32 v238, v154, v154
	v_fmac_f32_e32 v239, v155, v155
	v_fmac_f32_e32 v240, v156, v156
	v_fmac_f32_e32 v241, v157, v157
	v_fmac_f32_e32 v238, v166, v166
	v_fmac_f32_e32 v239, v167, v167
	v_fmac_f32_e32 v240, v168, v168
	v_fmac_f32_e32 v241, v169, v169
	v_add_f32_e32 v238, v238, v239
	v_add_f32_e32 v240, v240, v241
	v_add_f32_e32 v158, v238, v240
	s_nop 1
	v_add_f32_dpp v158, v158, v158 quad_perm:[1,0,3,2] row_mask:0xf bank_mask:0xf
	s_nop 1
	v_add_f32_dpp v158, v158, v158 quad_perm:[2,3,0,1] row_mask:0xf bank_mask:0xf
	s_nop 1
	v_add_f32_dpp v158, v158, v158 row_half_mirror row_mask:0xf bank_mask:0xf
	v_fmamk_f32 v158, v158, 0x3b800000, v206
	v_rsq_f32_e32 v158, v158
	s_waitcnt vmcnt(56)
	v_mov_b32_e32 v159, s0
	v_cndmask_b32_e32 v159, v210, v159, vcc
	v_add_u32_e32 v162, v159, v175
	v_ashrrev_i32_e32 v163, 31, v162
	v_lshlrev_b64 v[162:163], 13, v[162:163]
	v_lshl_add_u64 v[162:163], v[74:75], 0, v[162:163]
	s_mov_b64 s[0:1], -1
	v_pk_mul_f32 v[130:131], v[130:131], v[158:159] op_sel_hi:[1,0]
	v_lshlrev_b32_e32 v238, 16, v120
	v_and_b32_e32 v239, 0xffff0000, v120
	v_pk_mul_f32 v[130:131], v[130:131], v[238:239]
	v_cvt_pk_bf16_f32 v120, v130, v131
	v_pk_mul_f32 v[132:133], v[132:133], v[158:159] op_sel_hi:[1,0]
	v_lshlrev_b32_e32 v238, 16, v121
	v_and_b32_e32 v239, 0xffff0000, v121
	v_pk_mul_f32 v[132:133], v[132:133], v[238:239]
	v_cvt_pk_bf16_f32 v121, v132, v133
	v_pk_mul_f32 v[134:135], v[134:135], v[158:159] op_sel_hi:[1,0]
	v_lshlrev_b32_e32 v238, 16, v122
	v_and_b32_e32 v239, 0xffff0000, v122
	v_pk_mul_f32 v[134:135], v[134:135], v[238:239]
	v_cvt_pk_bf16_f32 v122, v134, v135
	v_pk_mul_f32 v[136:137], v[136:137], v[158:159] op_sel_hi:[1,0]
	v_lshlrev_b32_e32 v238, 16, v123
	v_and_b32_e32 v239, 0xffff0000, v123
	v_pk_mul_f32 v[136:137], v[136:137], v[238:239]
	v_cvt_pk_bf16_f32 v123, v136, v137
	global_store_dwordx4 v[162:163], v[120:123], off
	v_pk_mul_f32 v[138:139], v[138:139], v[158:159] op_sel_hi:[1,0]
	v_lshlrev_b32_e32 v238, 16, v124
	v_and_b32_e32 v239, 0xffff0000, v124
	v_pk_mul_f32 v[138:139], v[138:139], v[238:239]
	v_cvt_pk_bf16_f32 v124, v138, v139
	v_pk_mul_f32 v[140:141], v[140:141], v[158:159] op_sel_hi:[1,0]
	v_lshlrev_b32_e32 v238, 16, v125
	v_and_b32_e32 v239, 0xffff0000, v125
	v_pk_mul_f32 v[140:141], v[140:141], v[238:239]
	v_cvt_pk_bf16_f32 v125, v140, v141
	v_pk_mul_f32 v[142:143], v[142:143], v[158:159] op_sel_hi:[1,0]
	v_lshlrev_b32_e32 v238, 16, v126
	v_and_b32_e32 v239, 0xffff0000, v126
	v_pk_mul_f32 v[142:143], v[142:143], v[238:239]
	v_cvt_pk_bf16_f32 v126, v142, v143
	v_pk_mul_f32 v[144:145], v[144:145], v[158:159] op_sel_hi:[1,0]
	v_lshlrev_b32_e32 v238, 16, v127
	v_and_b32_e32 v239, 0xffff0000, v127
	v_pk_mul_f32 v[144:145], v[144:145], v[238:239]
	v_cvt_pk_bf16_f32 v127, v144, v145
	global_store_dwordx4 v[162:163], v[124:127], off offset:128
	v_pk_mul_f32 v[146:147], v[146:147], v[158:159] op_sel_hi:[1,0]
	v_lshlrev_b32_e32 v238, 16, v110
	v_and_b32_e32 v239, 0xffff0000, v110
	v_pk_mul_f32 v[146:147], v[146:147], v[238:239]
	v_cvt_pk_bf16_f32 v110, v146, v147
	v_pk_mul_f32 v[148:149], v[148:149], v[158:159] op_sel_hi:[1,0]
	v_lshlrev_b32_e32 v238, 16, v111
	v_and_b32_e32 v239, 0xffff0000, v111
	v_pk_mul_f32 v[148:149], v[148:149], v[238:239]
	v_cvt_pk_bf16_f32 v111, v148, v149
	v_pk_mul_f32 v[150:151], v[150:151], v[158:159] op_sel_hi:[1,0]
	v_lshlrev_b32_e32 v238, 16, v112
	v_and_b32_e32 v239, 0xffff0000, v112
	v_pk_mul_f32 v[150:151], v[150:151], v[238:239]
	v_cvt_pk_bf16_f32 v112, v150, v151
	v_pk_mul_f32 v[152:153], v[152:153], v[158:159] op_sel_hi:[1,0]
	v_lshlrev_b32_e32 v238, 16, v113
	v_and_b32_e32 v239, 0xffff0000, v113
	v_pk_mul_f32 v[152:153], v[152:153], v[238:239]
	v_cvt_pk_bf16_f32 v113, v152, v153
	global_store_dwordx4 v[162:163], v[110:113], off offset:256
	v_pk_mul_f32 v[154:155], v[154:155], v[158:159] op_sel_hi:[1,0]
	v_lshlrev_b32_e32 v238, 16, v88
	v_and_b32_e32 v239, 0xffff0000, v88
	v_pk_mul_f32 v[154:155], v[154:155], v[238:239]
	v_cvt_pk_bf16_f32 v88, v154, v155
	v_pk_mul_f32 v[156:157], v[156:157], v[158:159] op_sel_hi:[1,0]
	v_lshlrev_b32_e32 v238, 16, v89
	v_and_b32_e32 v239, 0xffff0000, v89
	v_pk_mul_f32 v[156:157], v[156:157], v[238:239]
	v_cvt_pk_bf16_f32 v89, v156, v157
	v_pk_mul_f32 v[166:167], v[166:167], v[158:159] op_sel_hi:[1,0]
	v_lshlrev_b32_e32 v238, 16, v116
	v_and_b32_e32 v239, 0xffff0000, v116
	v_pk_mul_f32 v[166:167], v[166:167], v[238:239]
	v_cvt_pk_bf16_f32 v116, v166, v167
	v_pk_mul_f32 v[168:169], v[168:169], v[158:159] op_sel_hi:[1,0]
	v_lshlrev_b32_e32 v238, 16, v117
	v_and_b32_e32 v239, 0xffff0000, v117
	v_pk_mul_f32 v[168:169], v[168:169], v[238:239]
	v_cvt_pk_bf16_f32 v117, v168, v169
	global_store_dwordx2 v[162:163], v[88:89], off offset:384
	global_store_dwordx2 v[162:163], v[116:117], off offset:392
	v_add_u32_e32 v238, s10, v217
	v_ashrrev_i32_e32 v239, 31, v238
	v_lshlrev_b64 v[238:239], 13, v[238:239]
	v_lshl_add_u64 v[238:239], v[78:79], 0, v[238:239]
	global_load_dwordx4 v[120:123], v[238:239], off
	global_load_dwordx4 v[124:127], v[238:239], off offset:128
	global_load_dwordx4 v[110:113], v[238:239], off offset:256
	global_load_dwordx2 v[88:89], v[238:239], off offset:384
	global_load_dwordx2 v[116:117], v[238:239], off offset:392
	s_sub_i32 s10, s17, s10
	s_cmp_gt_i32 s10, 31
	s_cbranch_scc1 .LBB0_307
	s_min_i32 s10, s10, 32
	v_add_f32_e32 v130, 0, v68
	v_cmp_gt_i32_e32 vcc, s10, v176
	v_cmp_gt_i32_e64 s[0:1], s10, v40
	v_and_b32_e32 v133, 0xffff0000, v215
	v_cndmask_b32_e32 v144, 0, v130, vcc
	v_add_f32_e32 v130, 0, v69
	v_cndmask_b32_e32 v143, 0, v130, vcc
	v_lshlrev_b32_e32 v130, 16, v201
	v_cndmask_b32_e32 v141, 0, v130, vcc
	v_and_b32_e32 v130, 0xffff0000, v201
	v_cndmask_b32_e32 v169, 0, v130, vcc
	v_cmp_gt_i32_e32 vcc, s10, v1
	v_lshlrev_b32_e32 v132, 16, v202
	v_cndmask_b32_e64 v138, 0, v132, s[0:1]
	v_cndmask_b32_e32 v130, 0, v104, vcc
	v_add_f32_e32 v142, v144, v130
	v_lshlrev_b32_e32 v130, 16, v215
	v_cndmask_b32_e32 v140, 0, v130, vcc
	v_cndmask_b32_e32 v131, 0, v105, vcc
	v_cndmask_b32_e64 v130, 0, v76, s[0:1]
	v_pk_add_f32 v[146:147], v[130:131], v[142:143]
	v_cndmask_b32_e64 v130, 0, v77, s[0:1]
	v_add_f32_e32 v241, v130, v147
	v_cndmask_b32_e32 v139, 0, v133, vcc
	v_and_b32_e32 v130, 0xffff0000, v202
	v_cmp_gt_i32_e32 vcc, s10, v3
	v_cndmask_b32_e64 v166, 0, v130, s[0:1]
	v_and_b32_e32 v131, 0xffff0000, v197
	v_cndmask_b32_e32 v130, 0, v72, vcc
	v_add_f32_e32 v239, v130, v146
	v_cndmask_b32_e32 v130, 0, v73, vcc
	v_add_f32_e32 v240, v130, v241
	v_lshlrev_b32_e32 v130, 16, v200
	v_cndmask_b32_e32 v135, 0, v130, vcc
	v_and_b32_e32 v130, 0xffff0000, v200
	v_cndmask_b32_e32 v159, 0, v130, vcc
	v_cmp_gt_i32_e32 vcc, s10, v43
	v_cmp_gt_i32_e64 s[0:1], s10, v42
	v_and_b32_e32 v133, 0xffff0000, v196
	v_cndmask_b32_e32 v130, 0, v70, vcc
	v_add_f32_e32 v173, v130, v239
	v_cndmask_b32_e32 v130, 0, v71, vcc
	v_add_f32_e32 v238, v130, v240
	v_lshlrev_b32_e32 v130, 16, v197
	v_cndmask_b32_e32 v134, 0, v130, vcc
	v_lshlrev_b32_e32 v130, 16, v198
	v_cndmask_b32_e64 v132, 0, v62, s[0:1]
	v_cndmask_b32_e32 v137, 0, v131, vcc
	v_cndmask_b32_e64 v136, 0, v130, s[0:1]
	v_and_b32_e32 v130, 0xffff0000, v198
	v_cmp_gt_i32_e32 vcc, s10, v45
	v_add_f32_e32 v171, v132, v173
	v_cndmask_b32_e64 v132, 0, v63, s[0:1]
	v_cndmask_b32_e64 v131, 0, v130, s[0:1]
	v_cndmask_b32_e32 v130, 0, v66, vcc
	v_add_f32_e32 v172, v132, v238
	v_add_f32_e32 v168, v130, v171
	v_cndmask_b32_e32 v130, 0, v67, vcc
	v_cmp_gt_i32_e64 s[0:1], s10, v44
	v_add_f32_e32 v170, v130, v172
	v_lshlrev_b32_e32 v130, 16, v196
	v_cndmask_b32_e64 v148, 0, v65, s[0:1]
	v_lshlrev_b32_e32 v132, 16, v225
	v_cndmask_b32_e64 v145, 0, v64, s[0:1]
	v_add_f32_e32 v167, v148, v170
	v_and_b32_e32 v148, 0xffff0000, v225
	v_cndmask_b32_e32 v130, 0, v130, vcc
	v_add_f32_e32 v145, v145, v168
	v_cndmask_b32_e32 v133, 0, v133, vcc
	v_cndmask_b32_e64 v132, 0, v132, s[0:1]
	v_cndmask_b32_e64 v158, 0, v148, s[0:1]
	s_mov_b64 s[0:1], 0
